# c39 + ssd3 entering-state scan software-pipelined 3 batches deep (loads of later segments in flight while earlier ones are folded in, same order of f32 math)
# baseline (speedup 1.0000x reference)
; template <int PASS>
; __device__ void ssd_item(const Params& p, int item, int l, unsigned char* smem) {
;     ...
;     if (PASS == 3) {
;         if (dir == 0) {
;             for (int e = 0; e < seg; ++e) { const float dc = __expf(SEGT[ibase + e]); const f32x4* src = (const f32x4*)(ST + (size_t)(ibase + e) * 8192);
; #pragma unroll
;                 for (int nt = 0; nt < 8; ++nt) S[nt] = S[nt] * dc + src[(w * 8 + nt) * 64 + lane]; }
;         } else {
;             for (int e = NSEG - 1; e > seg; --e) { const float dc = __expf(SEGT[ibase + e]); const f32x4* src = (const f32x4*)(ST + (size_t)(ibase + e) * 8192);
; #pragma unroll
;                 for (int nt = 0; nt < 8; ++nt) S[nt] = S[nt] * dc + src[(w * 8 + nt) * 64 + lane]; }
;         }
.LBB0_860:
	s_sub_u32 s98, 15, s12
	s_add_u32 s26, s92, s22
	s_addc_u32 s27, s93, s23
	global_load_dword v162, v81, s[26:27]
	s_mov_b32 s25, 0x1b078000
	s_add_u32 s22, s22, -4
	s_movk_i32 s26, 0x8000
	s_addc_u32 s23, s23, -1
	s_mov_b32 s27, -1
	v_lshl_add_u64 v[38:39], s[92:93], 0, v[34:35]
	v_add_co_u32_e32 v44, vcc, s25, v38
	s_mov_b32 s25, 0x1b079000
	s_nop 0
	v_addc_co_u32_e32 v45, vcc, 0, v39, vcc
	v_add_co_u32_e32 v46, vcc, s25, v38
	v_lshl_add_u64 v[34:35], v[34:35], 0, s[26:27]
	s_nop 0
	v_addc_co_u32_e32 v47, vcc, 0, v39, vcc
	global_load_dwordx4 v[120:123], v[46:47], off offset:-4096
	global_load_dwordx4 v[124:127], v[44:45], off offset:1024
	global_load_dwordx4 v[128:131], v[44:45], off offset:2048
	global_load_dwordx4 v[132:135], v[44:45], off offset:3072
	global_load_dwordx4 v[136:139], v[46:47], off
	global_load_dwordx4 v[140:143], v[46:47], off offset:1024
	global_load_dwordx4 v[144:147], v[46:47], off offset:2048
	global_load_dwordx4 v[148:151], v[46:47], off offset:3072
	s_add_i32 s98, s98, -1
	s_cmp_eq_u32 s98, 0
	s_cbranch_scc1 .Lsp1_d1A
	s_add_u32 s26, s92, s22
	s_addc_u32 s27, s93, s23
	global_load_dword v160, v81, s[26:27]
	s_mov_b32 s25, 0x1b078000
	s_add_u32 s22, s22, -4
	s_movk_i32 s26, 0x8000
	s_addc_u32 s23, s23, -1
	s_mov_b32 s27, -1
	v_lshl_add_u64 v[38:39], s[92:93], 0, v[34:35]
	v_add_co_u32_e32 v44, vcc, s25, v38
	s_mov_b32 s25, 0x1b079000
	s_nop 0
	v_addc_co_u32_e32 v45, vcc, 0, v39, vcc
	v_add_co_u32_e32 v46, vcc, s25, v38
	v_lshl_add_u64 v[34:35], v[34:35], 0, s[26:27]
	s_nop 0
	v_addc_co_u32_e32 v47, vcc, 0, v39, vcc
	global_load_dwordx4 v[152:155], v[46:47], off offset:-4096
	global_load_dwordx4 v[156:159], v[44:45], off offset:1024
	global_load_dwordx4 v[190:193], v[44:45], off offset:2048
	global_load_dwordx4 v[194:197], v[44:45], off offset:3072
	global_load_dwordx4 v[198:201], v[46:47], off
	global_load_dwordx4 v[202:205], v[46:47], off offset:1024
	global_load_dwordx4 v[236:239], v[46:47], off offset:2048
	global_load_dwordx4 v[244:247], v[46:47], off offset:3072
	s_add_i32 s98, s98, -1
	s_cmp_eq_u32 s98, 0
	s_cbranch_scc1 .Lsp1_d2A
	s_add_u32 s26, s92, s22
	s_addc_u32 s27, s93, s23
	global_load_dword v161, v81, s[26:27]
	s_mov_b32 s25, 0x1b078000
	s_add_u32 s22, s22, -4
	s_movk_i32 s26, 0x8000
	s_addc_u32 s23, s23, -1
	s_mov_b32 s27, -1
	v_lshl_add_u64 v[38:39], s[92:93], 0, v[34:35]
	v_add_co_u32_e32 v44, vcc, s25, v38
	s_mov_b32 s25, 0x1b079000
	s_nop 0
	v_addc_co_u32_e32 v45, vcc, 0, v39, vcc
	v_add_co_u32_e32 v46, vcc, s25, v38
	v_lshl_add_u64 v[34:35], v[34:35], 0, s[26:27]
	s_nop 0
	v_addc_co_u32_e32 v47, vcc, 0, v39, vcc
	global_load_dwordx4 v[56:59], v[46:47], off offset:-4096
	global_load_dwordx4 v[60:63], v[44:45], off offset:1024
	global_load_dwordx4 v[64:67], v[44:45], off offset:2048
	global_load_dwordx4 v[68:71], v[44:45], off offset:3072
	global_load_dwordx4 v[72:75], v[46:47], off
	global_load_dwordx4 v[76:79], v[46:47], off offset:1024
	global_load_dwordx4 v[82:85], v[46:47], off offset:2048
	global_load_dwordx4 v[86:89], v[46:47], off offset:3072
	s_add_i32 s98, s98, -1
.Lsp1_loop:
	s_waitcnt vmcnt(18)
	v_mul_f32_e32 v162, 0x3fb8aa3b, v162
	v_exp_f32_e32 v42, v162
	s_nop 0
	v_pk_fma_f32 v[2:3], v[2:3], v[42:43], v[122:123] op_sel_hi:[1,0,1]
	v_pk_fma_f32 v[0:1], v[0:1], v[42:43], v[120:121] op_sel_hi:[1,0,1]
	v_pk_fma_f32 v[6:7], v[6:7], v[42:43], v[126:127] op_sel_hi:[1,0,1]
	v_pk_fma_f32 v[4:5], v[4:5], v[42:43], v[124:125] op_sel_hi:[1,0,1]
	v_pk_fma_f32 v[10:11], v[10:11], v[42:43], v[130:131] op_sel_hi:[1,0,1]
	v_pk_fma_f32 v[8:9], v[8:9], v[42:43], v[128:129] op_sel_hi:[1,0,1]
	v_pk_fma_f32 v[14:15], v[14:15], v[42:43], v[134:135] op_sel_hi:[1,0,1]
	v_pk_fma_f32 v[12:13], v[12:13], v[42:43], v[132:133] op_sel_hi:[1,0,1]
	v_pk_fma_f32 v[18:19], v[18:19], v[42:43], v[138:139] op_sel_hi:[1,0,1]
	v_pk_fma_f32 v[16:17], v[16:17], v[42:43], v[136:137] op_sel_hi:[1,0,1]
	v_pk_fma_f32 v[22:23], v[22:23], v[42:43], v[142:143] op_sel_hi:[1,0,1]
	v_pk_fma_f32 v[20:21], v[20:21], v[42:43], v[140:141] op_sel_hi:[1,0,1]
	v_pk_fma_f32 v[26:27], v[26:27], v[42:43], v[146:147] op_sel_hi:[1,0,1]
	v_pk_fma_f32 v[24:25], v[24:25], v[42:43], v[144:145] op_sel_hi:[1,0,1]
	v_pk_fma_f32 v[30:31], v[30:31], v[42:43], v[150:151] op_sel_hi:[1,0,1]
	v_pk_fma_f32 v[28:29], v[28:29], v[42:43], v[148:149] op_sel_hi:[1,0,1]
	s_cmp_eq_u32 s98, 0
	s_cbranch_scc1 .Lsp1_d2B
	s_add_u32 s26, s92, s22
	s_addc_u32 s27, s93, s23
	global_load_dword v162, v81, s[26:27]
	s_mov_b32 s25, 0x1b078000
	s_add_u32 s22, s22, -4
	s_movk_i32 s26, 0x8000
	s_addc_u32 s23, s23, -1
	s_mov_b32 s27, -1
	v_lshl_add_u64 v[38:39], s[92:93], 0, v[34:35]
	v_add_co_u32_e32 v44, vcc, s25, v38
	s_mov_b32 s25, 0x1b079000
	s_nop 0
	v_addc_co_u32_e32 v45, vcc, 0, v39, vcc
	v_add_co_u32_e32 v46, vcc, s25, v38
	v_lshl_add_u64 v[34:35], v[34:35], 0, s[26:27]
	s_nop 0
	v_addc_co_u32_e32 v47, vcc, 0, v39, vcc
	global_load_dwordx4 v[120:123], v[46:47], off offset:-4096
	global_load_dwordx4 v[124:127], v[44:45], off offset:1024
	global_load_dwordx4 v[128:131], v[44:45], off offset:2048
	global_load_dwordx4 v[132:135], v[44:45], off offset:3072
	global_load_dwordx4 v[136:139], v[46:47], off
	global_load_dwordx4 v[140:143], v[46:47], off offset:1024
	global_load_dwordx4 v[144:147], v[46:47], off offset:2048
	global_load_dwordx4 v[148:151], v[46:47], off offset:3072
	s_add_i32 s98, s98, -1
	s_waitcnt vmcnt(18)
	v_mul_f32_e32 v160, 0x3fb8aa3b, v160
	v_exp_f32_e32 v42, v160
	s_nop 0
	v_pk_fma_f32 v[2:3], v[2:3], v[42:43], v[154:155] op_sel_hi:[1,0,1]
	v_pk_fma_f32 v[0:1], v[0:1], v[42:43], v[152:153] op_sel_hi:[1,0,1]
	v_pk_fma_f32 v[6:7], v[6:7], v[42:43], v[158:159] op_sel_hi:[1,0,1]
	v_pk_fma_f32 v[4:5], v[4:5], v[42:43], v[156:157] op_sel_hi:[1,0,1]
	v_pk_fma_f32 v[10:11], v[10:11], v[42:43], v[192:193] op_sel_hi:[1,0,1]
	v_pk_fma_f32 v[8:9], v[8:9], v[42:43], v[190:191] op_sel_hi:[1,0,1]
	v_pk_fma_f32 v[14:15], v[14:15], v[42:43], v[196:197] op_sel_hi:[1,0,1]
	v_pk_fma_f32 v[12:13], v[12:13], v[42:43], v[194:195] op_sel_hi:[1,0,1]
	v_pk_fma_f32 v[18:19], v[18:19], v[42:43], v[200:201] op_sel_hi:[1,0,1]
	v_pk_fma_f32 v[16:17], v[16:17], v[42:43], v[198:199] op_sel_hi:[1,0,1]
	v_pk_fma_f32 v[22:23], v[22:23], v[42:43], v[204:205] op_sel_hi:[1,0,1]
	v_pk_fma_f32 v[20:21], v[20:21], v[42:43], v[202:203] op_sel_hi:[1,0,1]
	v_pk_fma_f32 v[26:27], v[26:27], v[42:43], v[238:239] op_sel_hi:[1,0,1]
	v_pk_fma_f32 v[24:25], v[24:25], v[42:43], v[236:237] op_sel_hi:[1,0,1]
	v_pk_fma_f32 v[30:31], v[30:31], v[42:43], v[246:247] op_sel_hi:[1,0,1]
	v_pk_fma_f32 v[28:29], v[28:29], v[42:43], v[244:245] op_sel_hi:[1,0,1]
	s_cmp_eq_u32 s98, 0
	s_cbranch_scc1 .Lsp1_d2C
; template <int PASS>
; __device__ void ssd_item(const Params& p, int item, int l, unsigned char* smem) {
;     ...
;     if (PASS == 3) {
;         if (dir == 0) {
;             for (int e = 0; e < seg; ++e) { const float dc = __expf(SEGT[ibase + e]); const f32x4* src = (const f32x4*)(ST + (size_t)(ibase + e) * 8192);
; #pragma unroll
;                 for (int nt = 0; nt < 8; ++nt) S[nt] = S[nt] * dc + src[(w * 8 + nt) * 64 + lane]; }
;         } else {
;             for (int e = NSEG - 1; e > seg; --e) { const float dc = __expf(SEGT[ibase + e]); const f32x4* src = (const f32x4*)(ST + (size_t)(ibase + e) * 8192);
; #pragma unroll
;                 for (int nt = 0; nt < 8; ++nt) S[nt] = S[nt] * dc + src[(w * 8 + nt) * 64 + lane]; }
;         }
	s_add_u32 s26, s92, s22
	s_addc_u32 s27, s93, s23
	global_load_dword v160, v81, s[26:27]
	s_mov_b32 s25, 0x1b078000
	s_add_u32 s22, s22, -4
	s_movk_i32 s26, 0x8000
	s_addc_u32 s23, s23, -1
	s_mov_b32 s27, -1
	v_lshl_add_u64 v[38:39], s[92:93], 0, v[34:35]
	v_add_co_u32_e32 v44, vcc, s25, v38
	s_mov_b32 s25, 0x1b079000
	s_nop 0
	v_addc_co_u32_e32 v45, vcc, 0, v39, vcc
	v_add_co_u32_e32 v46, vcc, s25, v38
	v_lshl_add_u64 v[34:35], v[34:35], 0, s[26:27]
	s_nop 0
	v_addc_co_u32_e32 v47, vcc, 0, v39, vcc
	global_load_dwordx4 v[152:155], v[46:47], off offset:-4096
	global_load_dwordx4 v[156:159], v[44:45], off offset:1024
	global_load_dwordx4 v[190:193], v[44:45], off offset:2048
	global_load_dwordx4 v[194:197], v[44:45], off offset:3072
	global_load_dwordx4 v[198:201], v[46:47], off
	global_load_dwordx4 v[202:205], v[46:47], off offset:1024
	global_load_dwordx4 v[236:239], v[46:47], off offset:2048
	global_load_dwordx4 v[244:247], v[46:47], off offset:3072
	s_add_i32 s98, s98, -1
	s_waitcnt vmcnt(18)
	v_mul_f32_e32 v161, 0x3fb8aa3b, v161
	v_exp_f32_e32 v42, v161
	s_nop 0
	v_pk_fma_f32 v[2:3], v[2:3], v[42:43], v[58:59] op_sel_hi:[1,0,1]
	v_pk_fma_f32 v[0:1], v[0:1], v[42:43], v[56:57] op_sel_hi:[1,0,1]
	v_pk_fma_f32 v[6:7], v[6:7], v[42:43], v[62:63] op_sel_hi:[1,0,1]
	v_pk_fma_f32 v[4:5], v[4:5], v[42:43], v[60:61] op_sel_hi:[1,0,1]
	v_pk_fma_f32 v[10:11], v[10:11], v[42:43], v[66:67] op_sel_hi:[1,0,1]
	v_pk_fma_f32 v[8:9], v[8:9], v[42:43], v[64:65] op_sel_hi:[1,0,1]
	v_pk_fma_f32 v[14:15], v[14:15], v[42:43], v[70:71] op_sel_hi:[1,0,1]
	v_pk_fma_f32 v[12:13], v[12:13], v[42:43], v[68:69] op_sel_hi:[1,0,1]
	v_pk_fma_f32 v[18:19], v[18:19], v[42:43], v[74:75] op_sel_hi:[1,0,1]
	v_pk_fma_f32 v[16:17], v[16:17], v[42:43], v[72:73] op_sel_hi:[1,0,1]
	v_pk_fma_f32 v[22:23], v[22:23], v[42:43], v[78:79] op_sel_hi:[1,0,1]
	v_pk_fma_f32 v[20:21], v[20:21], v[42:43], v[76:77] op_sel_hi:[1,0,1]
	v_pk_fma_f32 v[26:27], v[26:27], v[42:43], v[84:85] op_sel_hi:[1,0,1]
	v_pk_fma_f32 v[24:25], v[24:25], v[42:43], v[82:83] op_sel_hi:[1,0,1]
	v_pk_fma_f32 v[30:31], v[30:31], v[42:43], v[88:89] op_sel_hi:[1,0,1]
	v_pk_fma_f32 v[28:29], v[28:29], v[42:43], v[86:87] op_sel_hi:[1,0,1]
	s_cmp_eq_u32 s98, 0
	s_cbranch_scc1 .Lsp1_d2A
	s_add_u32 s26, s92, s22
	s_addc_u32 s27, s93, s23
	global_load_dword v161, v81, s[26:27]
	s_mov_b32 s25, 0x1b078000
	s_add_u32 s22, s22, -4
	s_movk_i32 s26, 0x8000
	s_addc_u32 s23, s23, -1
	s_mov_b32 s27, -1
	v_lshl_add_u64 v[38:39], s[92:93], 0, v[34:35]
	v_add_co_u32_e32 v44, vcc, s25, v38
	s_mov_b32 s25, 0x1b079000
	s_nop 0
	v_addc_co_u32_e32 v45, vcc, 0, v39, vcc
	v_add_co_u32_e32 v46, vcc, s25, v38
	v_lshl_add_u64 v[34:35], v[34:35], 0, s[26:27]
	s_nop 0
	v_addc_co_u32_e32 v47, vcc, 0, v39, vcc
	global_load_dwordx4 v[56:59], v[46:47], off offset:-4096
	global_load_dwordx4 v[60:63], v[44:45], off offset:1024
	global_load_dwordx4 v[64:67], v[44:45], off offset:2048
	global_load_dwordx4 v[68:71], v[44:45], off offset:3072
	global_load_dwordx4 v[72:75], v[46:47], off
	global_load_dwordx4 v[76:79], v[46:47], off offset:1024
	global_load_dwordx4 v[82:85], v[46:47], off offset:2048
	global_load_dwordx4 v[86:89], v[46:47], off offset:3072
	s_add_i32 s98, s98, -1
	s_branch .Lsp1_loop
.Lsp1_d2A:
	s_waitcnt vmcnt(9)
	v_mul_f32_e32 v162, 0x3fb8aa3b, v162
	v_exp_f32_e32 v42, v162
	s_nop 0
	v_pk_fma_f32 v[2:3], v[2:3], v[42:43], v[122:123] op_sel_hi:[1,0,1]
	v_pk_fma_f32 v[0:1], v[0:1], v[42:43], v[120:121] op_sel_hi:[1,0,1]
	v_pk_fma_f32 v[6:7], v[6:7], v[42:43], v[126:127] op_sel_hi:[1,0,1]
	v_pk_fma_f32 v[4:5], v[4:5], v[42:43], v[124:125] op_sel_hi:[1,0,1]
	v_pk_fma_f32 v[10:11], v[10:11], v[42:43], v[130:131] op_sel_hi:[1,0,1]
	v_pk_fma_f32 v[8:9], v[8:9], v[42:43], v[128:129] op_sel_hi:[1,0,1]
	v_pk_fma_f32 v[14:15], v[14:15], v[42:43], v[134:135] op_sel_hi:[1,0,1]
	v_pk_fma_f32 v[12:13], v[12:13], v[42:43], v[132:133] op_sel_hi:[1,0,1]
	v_pk_fma_f32 v[18:19], v[18:19], v[42:43], v[138:139] op_sel_hi:[1,0,1]
	v_pk_fma_f32 v[16:17], v[16:17], v[42:43], v[136:137] op_sel_hi:[1,0,1]
	v_pk_fma_f32 v[22:23], v[22:23], v[42:43], v[142:143] op_sel_hi:[1,0,1]
	v_pk_fma_f32 v[20:21], v[20:21], v[42:43], v[140:141] op_sel_hi:[1,0,1]
	v_pk_fma_f32 v[26:27], v[26:27], v[42:43], v[146:147] op_sel_hi:[1,0,1]
	v_pk_fma_f32 v[24:25], v[24:25], v[42:43], v[144:145] op_sel_hi:[1,0,1]
	v_pk_fma_f32 v[30:31], v[30:31], v[42:43], v[150:151] op_sel_hi:[1,0,1]
	v_pk_fma_f32 v[28:29], v[28:29], v[42:43], v[148:149] op_sel_hi:[1,0,1]
	s_waitcnt vmcnt(0)
	v_mul_f32_e32 v160, 0x3fb8aa3b, v160
	v_exp_f32_e32 v42, v160
	s_nop 0
	v_pk_fma_f32 v[2:3], v[2:3], v[42:43], v[154:155] op_sel_hi:[1,0,1]
	v_pk_fma_f32 v[0:1], v[0:1], v[42:43], v[152:153] op_sel_hi:[1,0,1]
	v_pk_fma_f32 v[6:7], v[6:7], v[42:43], v[158:159] op_sel_hi:[1,0,1]
	v_pk_fma_f32 v[4:5], v[4:5], v[42:43], v[156:157] op_sel_hi:[1,0,1]
	v_pk_fma_f32 v[10:11], v[10:11], v[42:43], v[192:193] op_sel_hi:[1,0,1]
	v_pk_fma_f32 v[8:9], v[8:9], v[42:43], v[190:191] op_sel_hi:[1,0,1]
	v_pk_fma_f32 v[14:15], v[14:15], v[42:43], v[196:197] op_sel_hi:[1,0,1]
	v_pk_fma_f32 v[12:13], v[12:13], v[42:43], v[194:195] op_sel_hi:[1,0,1]
	v_pk_fma_f32 v[18:19], v[18:19], v[42:43], v[200:201] op_sel_hi:[1,0,1]
	v_pk_fma_f32 v[16:17], v[16:17], v[42:43], v[198:199] op_sel_hi:[1,0,1]
	v_pk_fma_f32 v[22:23], v[22:23], v[42:43], v[204:205] op_sel_hi:[1,0,1]
	v_pk_fma_f32 v[20:21], v[20:21], v[42:43], v[202:203] op_sel_hi:[1,0,1]
	v_pk_fma_f32 v[26:27], v[26:27], v[42:43], v[238:239] op_sel_hi:[1,0,1]
	v_pk_fma_f32 v[24:25], v[24:25], v[42:43], v[236:237] op_sel_hi:[1,0,1]
	v_pk_fma_f32 v[30:31], v[30:31], v[42:43], v[246:247] op_sel_hi:[1,0,1]
	v_pk_fma_f32 v[28:29], v[28:29], v[42:43], v[244:245] op_sel_hi:[1,0,1]
	s_branch .Lsp1_done
; template <int PASS>
; __device__ void ssd_item(const Params& p, int item, int l, unsigned char* smem) {
;     ...
;     if (PASS == 3) {
;         if (dir == 0) {
;             for (int e = 0; e < seg; ++e) { const float dc = __expf(SEGT[ibase + e]); const f32x4* src = (const f32x4*)(ST + (size_t)(ibase + e) * 8192);
; #pragma unroll
;                 for (int nt = 0; nt < 8; ++nt) S[nt] = S[nt] * dc + src[(w * 8 + nt) * 64 + lane]; }
;         } else {
;             for (int e = NSEG - 1; e > seg; --e) { const float dc = __expf(SEGT[ibase + e]); const f32x4* src = (const f32x4*)(ST + (size_t)(ibase + e) * 8192);
; #pragma unroll
;                 for (int nt = 0; nt < 8; ++nt) S[nt] = S[nt] * dc + src[(w * 8 + nt) * 64 + lane]; }
;         }
.Lsp1_d2B:
	s_waitcnt vmcnt(9)
	v_mul_f32_e32 v160, 0x3fb8aa3b, v160
	v_exp_f32_e32 v42, v160
	s_nop 0
	v_pk_fma_f32 v[2:3], v[2:3], v[42:43], v[154:155] op_sel_hi:[1,0,1]
	v_pk_fma_f32 v[0:1], v[0:1], v[42:43], v[152:153] op_sel_hi:[1,0,1]
	v_pk_fma_f32 v[6:7], v[6:7], v[42:43], v[158:159] op_sel_hi:[1,0,1]
	v_pk_fma_f32 v[4:5], v[4:5], v[42:43], v[156:157] op_sel_hi:[1,0,1]
	v_pk_fma_f32 v[10:11], v[10:11], v[42:43], v[192:193] op_sel_hi:[1,0,1]
	v_pk_fma_f32 v[8:9], v[8:9], v[42:43], v[190:191] op_sel_hi:[1,0,1]
	v_pk_fma_f32 v[14:15], v[14:15], v[42:43], v[196:197] op_sel_hi:[1,0,1]
	v_pk_fma_f32 v[12:13], v[12:13], v[42:43], v[194:195] op_sel_hi:[1,0,1]
	v_pk_fma_f32 v[18:19], v[18:19], v[42:43], v[200:201] op_sel_hi:[1,0,1]
	v_pk_fma_f32 v[16:17], v[16:17], v[42:43], v[198:199] op_sel_hi:[1,0,1]
	v_pk_fma_f32 v[22:23], v[22:23], v[42:43], v[204:205] op_sel_hi:[1,0,1]
	v_pk_fma_f32 v[20:21], v[20:21], v[42:43], v[202:203] op_sel_hi:[1,0,1]
	v_pk_fma_f32 v[26:27], v[26:27], v[42:43], v[238:239] op_sel_hi:[1,0,1]
	v_pk_fma_f32 v[24:25], v[24:25], v[42:43], v[236:237] op_sel_hi:[1,0,1]
	v_pk_fma_f32 v[30:31], v[30:31], v[42:43], v[246:247] op_sel_hi:[1,0,1]
	v_pk_fma_f32 v[28:29], v[28:29], v[42:43], v[244:245] op_sel_hi:[1,0,1]
	s_waitcnt vmcnt(0)
	v_mul_f32_e32 v161, 0x3fb8aa3b, v161
	v_exp_f32_e32 v42, v161
	s_nop 0
	v_pk_fma_f32 v[2:3], v[2:3], v[42:43], v[58:59] op_sel_hi:[1,0,1]
	v_pk_fma_f32 v[0:1], v[0:1], v[42:43], v[56:57] op_sel_hi:[1,0,1]
	v_pk_fma_f32 v[6:7], v[6:7], v[42:43], v[62:63] op_sel_hi:[1,0,1]
	v_pk_fma_f32 v[4:5], v[4:5], v[42:43], v[60:61] op_sel_hi:[1,0,1]
	v_pk_fma_f32 v[10:11], v[10:11], v[42:43], v[66:67] op_sel_hi:[1,0,1]
	v_pk_fma_f32 v[8:9], v[8:9], v[42:43], v[64:65] op_sel_hi:[1,0,1]
	v_pk_fma_f32 v[14:15], v[14:15], v[42:43], v[70:71] op_sel_hi:[1,0,1]
	v_pk_fma_f32 v[12:13], v[12:13], v[42:43], v[68:69] op_sel_hi:[1,0,1]
	v_pk_fma_f32 v[18:19], v[18:19], v[42:43], v[74:75] op_sel_hi:[1,0,1]
	v_pk_fma_f32 v[16:17], v[16:17], v[42:43], v[72:73] op_sel_hi:[1,0,1]
	v_pk_fma_f32 v[22:23], v[22:23], v[42:43], v[78:79] op_sel_hi:[1,0,1]
	v_pk_fma_f32 v[20:21], v[20:21], v[42:43], v[76:77] op_sel_hi:[1,0,1]
	v_pk_fma_f32 v[26:27], v[26:27], v[42:43], v[84:85] op_sel_hi:[1,0,1]
	v_pk_fma_f32 v[24:25], v[24:25], v[42:43], v[82:83] op_sel_hi:[1,0,1]
	v_pk_fma_f32 v[30:31], v[30:31], v[42:43], v[88:89] op_sel_hi:[1,0,1]
	v_pk_fma_f32 v[28:29], v[28:29], v[42:43], v[86:87] op_sel_hi:[1,0,1]
	s_branch .Lsp1_done
.Lsp1_d2C:
	s_waitcnt vmcnt(9)
	v_mul_f32_e32 v161, 0x3fb8aa3b, v161
	v_exp_f32_e32 v42, v161
	s_nop 0
	v_pk_fma_f32 v[2:3], v[2:3], v[42:43], v[58:59] op_sel_hi:[1,0,1]
	v_pk_fma_f32 v[0:1], v[0:1], v[42:43], v[56:57] op_sel_hi:[1,0,1]
	v_pk_fma_f32 v[6:7], v[6:7], v[42:43], v[62:63] op_sel_hi:[1,0,1]
	v_pk_fma_f32 v[4:5], v[4:5], v[42:43], v[60:61] op_sel_hi:[1,0,1]
	v_pk_fma_f32 v[10:11], v[10:11], v[42:43], v[66:67] op_sel_hi:[1,0,1]
	v_pk_fma_f32 v[8:9], v[8:9], v[42:43], v[64:65] op_sel_hi:[1,0,1]
	v_pk_fma_f32 v[14:15], v[14:15], v[42:43], v[70:71] op_sel_hi:[1,0,1]
	v_pk_fma_f32 v[12:13], v[12:13], v[42:43], v[68:69] op_sel_hi:[1,0,1]
	v_pk_fma_f32 v[18:19], v[18:19], v[42:43], v[74:75] op_sel_hi:[1,0,1]
	v_pk_fma_f32 v[16:17], v[16:17], v[42:43], v[72:73] op_sel_hi:[1,0,1]
	v_pk_fma_f32 v[22:23], v[22:23], v[42:43], v[78:79] op_sel_hi:[1,0,1]
	v_pk_fma_f32 v[20:21], v[20:21], v[42:43], v[76:77] op_sel_hi:[1,0,1]
	v_pk_fma_f32 v[26:27], v[26:27], v[42:43], v[84:85] op_sel_hi:[1,0,1]
	v_pk_fma_f32 v[24:25], v[24:25], v[42:43], v[82:83] op_sel_hi:[1,0,1]
	v_pk_fma_f32 v[30:31], v[30:31], v[42:43], v[88:89] op_sel_hi:[1,0,1]
	v_pk_fma_f32 v[28:29], v[28:29], v[42:43], v[86:87] op_sel_hi:[1,0,1]
	s_waitcnt vmcnt(0)
	v_mul_f32_e32 v162, 0x3fb8aa3b, v162
	v_exp_f32_e32 v42, v162
	s_nop 0
	v_pk_fma_f32 v[2:3], v[2:3], v[42:43], v[122:123] op_sel_hi:[1,0,1]
	v_pk_fma_f32 v[0:1], v[0:1], v[42:43], v[120:121] op_sel_hi:[1,0,1]
	v_pk_fma_f32 v[6:7], v[6:7], v[42:43], v[126:127] op_sel_hi:[1,0,1]
	v_pk_fma_f32 v[4:5], v[4:5], v[42:43], v[124:125] op_sel_hi:[1,0,1]
	v_pk_fma_f32 v[10:11], v[10:11], v[42:43], v[130:131] op_sel_hi:[1,0,1]
	v_pk_fma_f32 v[8:9], v[8:9], v[42:43], v[128:129] op_sel_hi:[1,0,1]
	v_pk_fma_f32 v[14:15], v[14:15], v[42:43], v[134:135] op_sel_hi:[1,0,1]
	v_pk_fma_f32 v[12:13], v[12:13], v[42:43], v[132:133] op_sel_hi:[1,0,1]
	v_pk_fma_f32 v[18:19], v[18:19], v[42:43], v[138:139] op_sel_hi:[1,0,1]
	v_pk_fma_f32 v[16:17], v[16:17], v[42:43], v[136:137] op_sel_hi:[1,0,1]
	v_pk_fma_f32 v[22:23], v[22:23], v[42:43], v[142:143] op_sel_hi:[1,0,1]
	v_pk_fma_f32 v[20:21], v[20:21], v[42:43], v[140:141] op_sel_hi:[1,0,1]
	v_pk_fma_f32 v[26:27], v[26:27], v[42:43], v[146:147] op_sel_hi:[1,0,1]
	v_pk_fma_f32 v[24:25], v[24:25], v[42:43], v[144:145] op_sel_hi:[1,0,1]
	v_pk_fma_f32 v[30:31], v[30:31], v[42:43], v[150:151] op_sel_hi:[1,0,1]
	v_pk_fma_f32 v[28:29], v[28:29], v[42:43], v[148:149] op_sel_hi:[1,0,1]
	s_branch .Lsp1_done
.Lsp1_d1A:
	s_waitcnt vmcnt(0)
	v_mul_f32_e32 v162, 0x3fb8aa3b, v162
	v_exp_f32_e32 v42, v162
	s_nop 0
	v_pk_fma_f32 v[2:3], v[2:3], v[42:43], v[122:123] op_sel_hi:[1,0,1]
	v_pk_fma_f32 v[0:1], v[0:1], v[42:43], v[120:121] op_sel_hi:[1,0,1]
	v_pk_fma_f32 v[6:7], v[6:7], v[42:43], v[126:127] op_sel_hi:[1,0,1]
	v_pk_fma_f32 v[4:5], v[4:5], v[42:43], v[124:125] op_sel_hi:[1,0,1]
	v_pk_fma_f32 v[10:11], v[10:11], v[42:43], v[130:131] op_sel_hi:[1,0,1]
	v_pk_fma_f32 v[8:9], v[8:9], v[42:43], v[128:129] op_sel_hi:[1,0,1]
	v_pk_fma_f32 v[14:15], v[14:15], v[42:43], v[134:135] op_sel_hi:[1,0,1]
	v_pk_fma_f32 v[12:13], v[12:13], v[42:43], v[132:133] op_sel_hi:[1,0,1]
	v_pk_fma_f32 v[18:19], v[18:19], v[42:43], v[138:139] op_sel_hi:[1,0,1]
	v_pk_fma_f32 v[16:17], v[16:17], v[42:43], v[136:137] op_sel_hi:[1,0,1]
	v_pk_fma_f32 v[22:23], v[22:23], v[42:43], v[142:143] op_sel_hi:[1,0,1]
	v_pk_fma_f32 v[20:21], v[20:21], v[42:43], v[140:141] op_sel_hi:[1,0,1]
	v_pk_fma_f32 v[26:27], v[26:27], v[42:43], v[146:147] op_sel_hi:[1,0,1]
	v_pk_fma_f32 v[24:25], v[24:25], v[42:43], v[144:145] op_sel_hi:[1,0,1]
	v_pk_fma_f32 v[30:31], v[30:31], v[42:43], v[150:151] op_sel_hi:[1,0,1]
	v_pk_fma_f32 v[28:29], v[28:29], v[42:43], v[148:149] op_sel_hi:[1,0,1]

; template <int PASS>
; __device__ void ssd_item(const Params& p, int item, int l, unsigned char* smem) {
;     ...
;     if (PASS == 3) {
;         if (dir == 0) {
;             for (int e = 0; e < seg; ++e) { const float dc = __expf(SEGT[ibase + e]); const f32x4* src = (const f32x4*)(ST + (size_t)(ibase + e) * 8192);
; #pragma unroll
;                 for (int nt = 0; nt < 8; ++nt) S[nt] = S[nt] * dc + src[(w * 8 + nt) * 64 + lane]; }
;         } else {
.LBB0_865:
	s_mov_b32 s98, s22
	s_add_u32 s26, s92, s23
	s_addc_u32 s27, s93, s24
	global_load_dword v162, v81, s[26:27]
	s_mov_b32 s25, 0x1b000000
	s_add_u32 s23, s23, 4
	s_addc_u32 s24, s24, 0
	v_lshl_add_u64 v[38:39], s[92:93], 0, v[34:35]
	v_add_co_u32_e32 v44, vcc, s25, v38
	s_mov_b32 s25, 0x1b001000
	s_nop 0
	v_addc_co_u32_e32 v45, vcc, 0, v39, vcc
	v_add_co_u32_e32 v46, vcc, s25, v38
	v_lshl_add_u64 v[34:35], v[34:35], 0, s[14:15]
	s_nop 0
	v_addc_co_u32_e32 v47, vcc, 0, v39, vcc
	global_load_dwordx4 v[120:123], v[46:47], off offset:-4096
	global_load_dwordx4 v[124:127], v[44:45], off offset:1024
	global_load_dwordx4 v[128:131], v[44:45], off offset:2048
	global_load_dwordx4 v[132:135], v[44:45], off offset:3072
	global_load_dwordx4 v[136:139], v[46:47], off
	global_load_dwordx4 v[140:143], v[46:47], off offset:1024
	global_load_dwordx4 v[144:147], v[46:47], off offset:2048
	global_load_dwordx4 v[148:151], v[46:47], off offset:3072
	s_add_i32 s98, s98, -1
	s_cmp_eq_u32 s98, 0
	s_cbranch_scc1 .Lsp2_d1A
	s_add_u32 s26, s92, s23
	s_addc_u32 s27, s93, s24
	global_load_dword v160, v81, s[26:27]
	s_mov_b32 s25, 0x1b000000
	s_add_u32 s23, s23, 4
	s_addc_u32 s24, s24, 0
	v_lshl_add_u64 v[38:39], s[92:93], 0, v[34:35]
	v_add_co_u32_e32 v44, vcc, s25, v38
	s_mov_b32 s25, 0x1b001000
	s_nop 0
	v_addc_co_u32_e32 v45, vcc, 0, v39, vcc
	v_add_co_u32_e32 v46, vcc, s25, v38
	v_lshl_add_u64 v[34:35], v[34:35], 0, s[14:15]
	s_nop 0
	v_addc_co_u32_e32 v47, vcc, 0, v39, vcc
	global_load_dwordx4 v[152:155], v[46:47], off offset:-4096
	global_load_dwordx4 v[156:159], v[44:45], off offset:1024
	global_load_dwordx4 v[190:193], v[44:45], off offset:2048
	global_load_dwordx4 v[194:197], v[44:45], off offset:3072
	global_load_dwordx4 v[198:201], v[46:47], off
	global_load_dwordx4 v[202:205], v[46:47], off offset:1024
	global_load_dwordx4 v[236:239], v[46:47], off offset:2048
	global_load_dwordx4 v[244:247], v[46:47], off offset:3072
	s_add_i32 s98, s98, -1
	s_cmp_eq_u32 s98, 0
	s_cbranch_scc1 .Lsp2_d2A
	s_add_u32 s26, s92, s23
	s_addc_u32 s27, s93, s24
	global_load_dword v161, v81, s[26:27]
	s_mov_b32 s25, 0x1b000000
	s_add_u32 s23, s23, 4
	s_addc_u32 s24, s24, 0
	v_lshl_add_u64 v[38:39], s[92:93], 0, v[34:35]
	v_add_co_u32_e32 v44, vcc, s25, v38
	s_mov_b32 s25, 0x1b001000
	s_nop 0
	v_addc_co_u32_e32 v45, vcc, 0, v39, vcc
	v_add_co_u32_e32 v46, vcc, s25, v38
	v_lshl_add_u64 v[34:35], v[34:35], 0, s[14:15]
	s_nop 0
	v_addc_co_u32_e32 v47, vcc, 0, v39, vcc
	global_load_dwordx4 v[56:59], v[46:47], off offset:-4096
	global_load_dwordx4 v[60:63], v[44:45], off offset:1024
	global_load_dwordx4 v[64:67], v[44:45], off offset:2048
	global_load_dwordx4 v[68:71], v[44:45], off offset:3072
	global_load_dwordx4 v[72:75], v[46:47], off
	global_load_dwordx4 v[76:79], v[46:47], off offset:1024
	global_load_dwordx4 v[82:85], v[46:47], off offset:2048
	global_load_dwordx4 v[86:89], v[46:47], off offset:3072
	s_add_i32 s98, s98, -1
; template <int PASS>
; __device__ void ssd_item(const Params& p, int item, int l, unsigned char* smem) {
;     ...
;     if (PASS == 3) {
;         if (dir == 0) {
;             for (int e = 0; e < seg; ++e) { const float dc = __expf(SEGT[ibase + e]); const f32x4* src = (const f32x4*)(ST + (size_t)(ibase + e) * 8192);
; #pragma unroll
;                 for (int nt = 0; nt < 8; ++nt) S[nt] = S[nt] * dc + src[(w * 8 + nt) * 64 + lane]; }
;         } else {
.Lsp2_loop:
	s_waitcnt vmcnt(18)
	v_mul_f32_e32 v162, 0x3fb8aa3b, v162
	v_exp_f32_e32 v42, v162
	s_nop 0
	v_pk_fma_f32 v[2:3], v[2:3], v[42:43], v[122:123] op_sel_hi:[1,0,1]
	v_pk_fma_f32 v[0:1], v[0:1], v[42:43], v[120:121] op_sel_hi:[1,0,1]
	v_pk_fma_f32 v[6:7], v[6:7], v[42:43], v[126:127] op_sel_hi:[1,0,1]
	v_pk_fma_f32 v[4:5], v[4:5], v[42:43], v[124:125] op_sel_hi:[1,0,1]
	v_pk_fma_f32 v[10:11], v[10:11], v[42:43], v[130:131] op_sel_hi:[1,0,1]
	v_pk_fma_f32 v[8:9], v[8:9], v[42:43], v[128:129] op_sel_hi:[1,0,1]
	v_pk_fma_f32 v[14:15], v[14:15], v[42:43], v[134:135] op_sel_hi:[1,0,1]
	v_pk_fma_f32 v[12:13], v[12:13], v[42:43], v[132:133] op_sel_hi:[1,0,1]
	v_pk_fma_f32 v[18:19], v[18:19], v[42:43], v[138:139] op_sel_hi:[1,0,1]
	v_pk_fma_f32 v[16:17], v[16:17], v[42:43], v[136:137] op_sel_hi:[1,0,1]
	v_pk_fma_f32 v[22:23], v[22:23], v[42:43], v[142:143] op_sel_hi:[1,0,1]
	v_pk_fma_f32 v[20:21], v[20:21], v[42:43], v[140:141] op_sel_hi:[1,0,1]
	v_pk_fma_f32 v[26:27], v[26:27], v[42:43], v[146:147] op_sel_hi:[1,0,1]
	v_pk_fma_f32 v[24:25], v[24:25], v[42:43], v[144:145] op_sel_hi:[1,0,1]
	v_pk_fma_f32 v[30:31], v[30:31], v[42:43], v[150:151] op_sel_hi:[1,0,1]
	v_pk_fma_f32 v[28:29], v[28:29], v[42:43], v[148:149] op_sel_hi:[1,0,1]
	s_cmp_eq_u32 s98, 0
	s_cbranch_scc1 .Lsp2_d2B
	s_add_u32 s26, s92, s23
	s_addc_u32 s27, s93, s24
	global_load_dword v162, v81, s[26:27]
	s_mov_b32 s25, 0x1b000000
	s_add_u32 s23, s23, 4
	s_addc_u32 s24, s24, 0
	v_lshl_add_u64 v[38:39], s[92:93], 0, v[34:35]
	v_add_co_u32_e32 v44, vcc, s25, v38
	s_mov_b32 s25, 0x1b001000
	s_nop 0
	v_addc_co_u32_e32 v45, vcc, 0, v39, vcc
	v_add_co_u32_e32 v46, vcc, s25, v38
	v_lshl_add_u64 v[34:35], v[34:35], 0, s[14:15]
	s_nop 0
	v_addc_co_u32_e32 v47, vcc, 0, v39, vcc
	global_load_dwordx4 v[120:123], v[46:47], off offset:-4096
	global_load_dwordx4 v[124:127], v[44:45], off offset:1024
	global_load_dwordx4 v[128:131], v[44:45], off offset:2048
	global_load_dwordx4 v[132:135], v[44:45], off offset:3072
	global_load_dwordx4 v[136:139], v[46:47], off
	global_load_dwordx4 v[140:143], v[46:47], off offset:1024
	global_load_dwordx4 v[144:147], v[46:47], off offset:2048
	global_load_dwordx4 v[148:151], v[46:47], off offset:3072
	s_add_i32 s98, s98, -1
	s_waitcnt vmcnt(18)
	v_mul_f32_e32 v160, 0x3fb8aa3b, v160
	v_exp_f32_e32 v42, v160
	s_nop 0
	v_pk_fma_f32 v[2:3], v[2:3], v[42:43], v[154:155] op_sel_hi:[1,0,1]
	v_pk_fma_f32 v[0:1], v[0:1], v[42:43], v[152:153] op_sel_hi:[1,0,1]
	v_pk_fma_f32 v[6:7], v[6:7], v[42:43], v[158:159] op_sel_hi:[1,0,1]
	v_pk_fma_f32 v[4:5], v[4:5], v[42:43], v[156:157] op_sel_hi:[1,0,1]
	v_pk_fma_f32 v[10:11], v[10:11], v[42:43], v[192:193] op_sel_hi:[1,0,1]
	v_pk_fma_f32 v[8:9], v[8:9], v[42:43], v[190:191] op_sel_hi:[1,0,1]
	v_pk_fma_f32 v[14:15], v[14:15], v[42:43], v[196:197] op_sel_hi:[1,0,1]
	v_pk_fma_f32 v[12:13], v[12:13], v[42:43], v[194:195] op_sel_hi:[1,0,1]
	v_pk_fma_f32 v[18:19], v[18:19], v[42:43], v[200:201] op_sel_hi:[1,0,1]
	v_pk_fma_f32 v[16:17], v[16:17], v[42:43], v[198:199] op_sel_hi:[1,0,1]
	v_pk_fma_f32 v[22:23], v[22:23], v[42:43], v[204:205] op_sel_hi:[1,0,1]
	v_pk_fma_f32 v[20:21], v[20:21], v[42:43], v[202:203] op_sel_hi:[1,0,1]
	v_pk_fma_f32 v[26:27], v[26:27], v[42:43], v[238:239] op_sel_hi:[1,0,1]
	v_pk_fma_f32 v[24:25], v[24:25], v[42:43], v[236:237] op_sel_hi:[1,0,1]
	v_pk_fma_f32 v[30:31], v[30:31], v[42:43], v[246:247] op_sel_hi:[1,0,1]
	v_pk_fma_f32 v[28:29], v[28:29], v[42:43], v[244:245] op_sel_hi:[1,0,1]
	s_cmp_eq_u32 s98, 0
	s_cbranch_scc1 .Lsp2_d2C
	s_add_u32 s26, s92, s23
	s_addc_u32 s27, s93, s24
	global_load_dword v160, v81, s[26:27]
	s_mov_b32 s25, 0x1b000000
	s_add_u32 s23, s23, 4
	s_addc_u32 s24, s24, 0
	v_lshl_add_u64 v[38:39], s[92:93], 0, v[34:35]
	v_add_co_u32_e32 v44, vcc, s25, v38
	s_mov_b32 s25, 0x1b001000
	s_nop 0
	v_addc_co_u32_e32 v45, vcc, 0, v39, vcc
	v_add_co_u32_e32 v46, vcc, s25, v38
	v_lshl_add_u64 v[34:35], v[34:35], 0, s[14:15]
	s_nop 0
	v_addc_co_u32_e32 v47, vcc, 0, v39, vcc
	global_load_dwordx4 v[152:155], v[46:47], off offset:-4096
	global_load_dwordx4 v[156:159], v[44:45], off offset:1024
	global_load_dwordx4 v[190:193], v[44:45], off offset:2048
	global_load_dwordx4 v[194:197], v[44:45], off offset:3072
	global_load_dwordx4 v[198:201], v[46:47], off
	global_load_dwordx4 v[202:205], v[46:47], off offset:1024
	global_load_dwordx4 v[236:239], v[46:47], off offset:2048
	global_load_dwordx4 v[244:247], v[46:47], off offset:3072
	s_add_i32 s98, s98, -1
	s_waitcnt vmcnt(18)
	v_mul_f32_e32 v161, 0x3fb8aa3b, v161
	v_exp_f32_e32 v42, v161
	s_nop 0
	v_pk_fma_f32 v[2:3], v[2:3], v[42:43], v[58:59] op_sel_hi:[1,0,1]
	v_pk_fma_f32 v[0:1], v[0:1], v[42:43], v[56:57] op_sel_hi:[1,0,1]
	v_pk_fma_f32 v[6:7], v[6:7], v[42:43], v[62:63] op_sel_hi:[1,0,1]
	v_pk_fma_f32 v[4:5], v[4:5], v[42:43], v[60:61] op_sel_hi:[1,0,1]
	v_pk_fma_f32 v[10:11], v[10:11], v[42:43], v[66:67] op_sel_hi:[1,0,1]
	v_pk_fma_f32 v[8:9], v[8:9], v[42:43], v[64:65] op_sel_hi:[1,0,1]
	v_pk_fma_f32 v[14:15], v[14:15], v[42:43], v[70:71] op_sel_hi:[1,0,1]
	v_pk_fma_f32 v[12:13], v[12:13], v[42:43], v[68:69] op_sel_hi:[1,0,1]
	v_pk_fma_f32 v[18:19], v[18:19], v[42:43], v[74:75] op_sel_hi:[1,0,1]
	v_pk_fma_f32 v[16:17], v[16:17], v[42:43], v[72:73] op_sel_hi:[1,0,1]
	v_pk_fma_f32 v[22:23], v[22:23], v[42:43], v[78:79] op_sel_hi:[1,0,1]
	v_pk_fma_f32 v[20:21], v[20:21], v[42:43], v[76:77] op_sel_hi:[1,0,1]
	v_pk_fma_f32 v[26:27], v[26:27], v[42:43], v[84:85] op_sel_hi:[1,0,1]
	v_pk_fma_f32 v[24:25], v[24:25], v[42:43], v[82:83] op_sel_hi:[1,0,1]
	v_pk_fma_f32 v[30:31], v[30:31], v[42:43], v[88:89] op_sel_hi:[1,0,1]
	v_pk_fma_f32 v[28:29], v[28:29], v[42:43], v[86:87] op_sel_hi:[1,0,1]
	s_cmp_eq_u32 s98, 0
	s_cbranch_scc1 .Lsp2_d2A
	s_add_u32 s26, s92, s23
	s_addc_u32 s27, s93, s24
	global_load_dword v161, v81, s[26:27]
	s_mov_b32 s25, 0x1b000000
	s_add_u32 s23, s23, 4
	s_addc_u32 s24, s24, 0
	v_lshl_add_u64 v[38:39], s[92:93], 0, v[34:35]
	v_add_co_u32_e32 v44, vcc, s25, v38
	s_mov_b32 s25, 0x1b001000
	s_nop 0
	v_addc_co_u32_e32 v45, vcc, 0, v39, vcc
	v_add_co_u32_e32 v46, vcc, s25, v38
	v_lshl_add_u64 v[34:35], v[34:35], 0, s[14:15]
	s_nop 0
	v_addc_co_u32_e32 v47, vcc, 0, v39, vcc
	global_load_dwordx4 v[56:59], v[46:47], off offset:-4096
	global_load_dwordx4 v[60:63], v[44:45], off offset:1024
	global_load_dwordx4 v[64:67], v[44:45], off offset:2048
	global_load_dwordx4 v[68:71], v[44:45], off offset:3072
	global_load_dwordx4 v[72:75], v[46:47], off
	global_load_dwordx4 v[76:79], v[46:47], off offset:1024
	global_load_dwordx4 v[82:85], v[46:47], off offset:2048
	global_load_dwordx4 v[86:89], v[46:47], off offset:3072
	s_add_i32 s98, s98, -1
	s_branch .Lsp2_loop

; template <int PASS>
; __device__ void ssd_item(const Params& p, int item, int l, unsigned char* smem) {
;     ...
;     if (PASS == 3) {
;         if (dir == 0) {
;             for (int e = 0; e < seg; ++e) { const float dc = __expf(SEGT[ibase + e]); const f32x4* src = (const f32x4*)(ST + (size_t)(ibase + e) * 8192);
; #pragma unroll
;                 for (int nt = 0; nt < 8; ++nt) S[nt] = S[nt] * dc + src[(w * 8 + nt) * 64 + lane]; }
;         } else {
.Lsp2_d1A:
	s_waitcnt vmcnt(0)
	v_mul_f32_e32 v162, 0x3fb8aa3b, v162
	v_exp_f32_e32 v42, v162
	s_nop 0
	v_pk_fma_f32 v[2:3], v[2:3], v[42:43], v[122:123] op_sel_hi:[1,0,1]
	v_pk_fma_f32 v[0:1], v[0:1], v[42:43], v[120:121] op_sel_hi:[1,0,1]
	v_pk_fma_f32 v[6:7], v[6:7], v[42:43], v[126:127] op_sel_hi:[1,0,1]
	v_pk_fma_f32 v[4:5], v[4:5], v[42:43], v[124:125] op_sel_hi:[1,0,1]
	v_pk_fma_f32 v[10:11], v[10:11], v[42:43], v[130:131] op_sel_hi:[1,0,1]
	v_pk_fma_f32 v[8:9], v[8:9], v[42:43], v[128:129] op_sel_hi:[1,0,1]
	v_pk_fma_f32 v[14:15], v[14:15], v[42:43], v[134:135] op_sel_hi:[1,0,1]
	v_pk_fma_f32 v[12:13], v[12:13], v[42:43], v[132:133] op_sel_hi:[1,0,1]
	v_pk_fma_f32 v[18:19], v[18:19], v[42:43], v[138:139] op_sel_hi:[1,0,1]
	v_pk_fma_f32 v[16:17], v[16:17], v[42:43], v[136:137] op_sel_hi:[1,0,1]
	v_pk_fma_f32 v[22:23], v[22:23], v[42:43], v[142:143] op_sel_hi:[1,0,1]
	v_pk_fma_f32 v[20:21], v[20:21], v[42:43], v[140:141] op_sel_hi:[1,0,1]
	v_pk_fma_f32 v[26:27], v[26:27], v[42:43], v[146:147] op_sel_hi:[1,0,1]
	v_pk_fma_f32 v[24:25], v[24:25], v[42:43], v[144:145] op_sel_hi:[1,0,1]
	v_pk_fma_f32 v[30:31], v[30:31], v[42:43], v[150:151] op_sel_hi:[1,0,1]
	v_pk_fma_f32 v[28:29], v[28:29], v[42:43], v[148:149] op_sel_hi:[1,0,1]
	s_branch .LBB0_868
